# attention stagger: map-1 waves sleep 128 cycles per step
# baseline (speedup 1.0000x reference)
.LBB0_310:
	s_and_b64 vcc, exec, s[40:41]
	s_cbranch_vccz .Lat_nostag
	s_sleep 2
